# attention tile loop: K/V row pointers carried instead of rebuilt with 64-bit multiplies
# speedup vs baseline: 1.0284x; 1.0044x over previous
; #define AT_LOAD(tl_) do { _Pragma("unroll") for (int i_ = 0; i_ < 2; ++i_) { const bf16_t* b_ = proj + (size_t)(kt0 + (tl_) * 64 + skey + 32 * i_) * PP + 64 * kvh + sdc; \
;     rk[i_] = *(const u32x4*)(b_ + C_K); rv[i_] = *(const u32x4*)(b_ + C_V); } } while (0)
; #define AT_STORE(buf_) do { _Pragma("unroll") for (int i_ = 0; i_ < 2; ++i_) { *(u32x4*)(Ks + (buf_) * 64 * 72 + (skey + 32 * i_) * 72 + sdc) = rk[i_]; \
;     *(u32x4*)(Vs + (buf_) * 64 * 72 + (skey + 32 * i_) * 72 + sdc) = rv[i_]; } } while (0)
; DI void attn_unit(const Params& p, int unit, unsigned char* lds) {
;   int tid = threadIdx.x; asm volatile("" : "+v"(tid)); const int wid = tid >> 6, lane = tid & 63, r = lane & 31, hh = lane >> 5;
;   int seqi, kvh, kvc, qblk;
;   if (unit < 2048) { qblk = unit & 127; const int g = unit >> 7; kvc = g & 3; kvh = (g >> 2) & 1; seqi = g >> 3; }
;   else { const int u = unit - 2048; qblk = u & 31; const int g = u >> 5; kvh = g & 1; seqi = 2 + (g >> 1); kvc = 0; }
;   const int s0 = seqi < 2 ? seqi * 16384 : T_PROMPT + (seqi - 2) * 4096;
;   const int tq0 = s0 + qblk * 128 + 32 * wid, kt0 = s0 + kvc * 4096;
;   bf16_t* proj = (bf16_t*)(p.ws + WS_PROJ);
;   bf16_t* Ks = (bf16_t*)lds; bf16_t* Vs = Ks + 2 * 64 * 72;
;   bf16x8 Qf[2][4];
; #pragma unroll
;   for (int g = 0; g < 2; ++g)
; #pragma unroll
;     for (int ks = 0; ks < 4; ++ks) Qf[g][ks] = *(const bf16x8*)(proj + (size_t)(tq0 + r) * PP + C_Q + 64 * (2 * kvh + g) + 16 * ks + 8 * hh);
;   f32x16 O[2][2];
; #pragma unroll
;   for (int a = 0; a < 2; ++a)
; #pragma unroll
;     for (int b = 0; b < 2; ++b)
; #pragma unroll
;       for (int i = 0; i < 16; ++i) O[a][b][i] = 0.f;
;   float lsum[2] = {0.f, 0.f};
;   u32x4 rk[2], rv[2];
;   const int skey = tid >> 3, sdc = (tid & 7) * 8;
;     ...
;   AT_LOAD(0); AT_STORE(0); __syncthreads();
;   const int gi = (lane >> 4) & 1, qq = (lane & 15) >> 2, pp = lane & 3;
;   const int troff = (4 * hh + qq) * 72 + 16 * gi + 4 * pp;
;   for (int tl = 0; tl < 64; ++tl) {
;     { const int tn_ = tl + 1 < 64 ? tl + 1 : 63; AT_LOAD(tn_); }
.LBB0_98:
	s_lshl_b32 s3, s7, 12
	s_and_b32 s35, s14, 1
	s_lshl_b32 s2, s7, 14
	s_addk_i32 s3, 0x6000
	s_cmp_lt_i32 s7, 2
	s_cselect_b32 s2, s2, s3
	s_lshl_b32 s3, s5, 7
	v_ashrrev_i32_e32 v1, 1, v0
	v_and_b32_e32 v1, 0xffffffe0, v1
	s_add_i32 s3, s2, s3
	v_and_b32_e32 v202, 31, v0
	v_add_u32_e32 v164, s3, v1
	v_bfe_u32 v201, v0, 5, 1
	v_or_b32_e32 v1, v164, v202
	v_mov_b64_e32 v[2:3], s[46:47]
	v_mad_i64_i32 v[162:163], s[6:7], v1, s12, v[2:3]
	v_lshlrev_b32_e32 v160, 4, v201
	s_lshl_b32 s3, s34, 12
	v_lshl_add_u64 v[2:3], v[162:163], 0, v[160:161]
	s_lshl_b32 s84, s35, 8
	s_lshl_b32 s21, s35, 7
	v_lshl_add_u64 v[2:3], v[2:3], 0, s[84:85]
	s_add_i32 s2, s2, s3
	global_load_dwordx4 v[116:119], v[2:3], off offset:3584
	global_load_dwordx4 v[108:111], v[2:3], off offset:3616
	global_load_dwordx4 v[100:103], v[2:3], off offset:3648
	global_load_dwordx4 v[96:99], v[2:3], off offset:3680
	global_load_dwordx4 v[124:127], v[2:3], off offset:3712
	global_load_dwordx4 v[120:123], v[2:3], off offset:3744
	global_load_dwordx4 v[112:115], v[2:3], off offset:3776
	global_load_dwordx4 v[104:107], v[2:3], off offset:3808
	s_add_u32 s6, s46, s21
	v_lshlrev_b32_e32 v2, 4, v0
	v_ashrrev_i32_e32 v1, 3, v0
	s_addc_u32 s7, s47, 0
	v_and_b32_e32 v18, 0x70, v2
	v_mov_b32_e32 v19, v161
	v_add_u32_e32 v203, s2, v1
	v_lshl_add_u64 v[166:167], s[6:7], 0, v[18:19]
	v_mad_i64_i32 v[2:3], s[6:7], v203, s12, v[166:167]
	v_add_co_u32_e32 v6, vcc, s13, v2
	v_add_u32_e32 v10, 32, v203
	s_nop 0
	v_addc_co_u32_e32 v7, vcc, 0, v3, vcc
	v_mad_i64_i32 v[10:11], s[6:7], v10, s12, v[166:167]
	v_add_co_u32_e32 v14, vcc, s13, v10
	global_load_dwordx4 v[2:5], v[6:7], off
	s_nop 0
	global_load_dwordx4 v[6:9], v[6:7], off offset:256
	v_addc_co_u32_e32 v15, vcc, 0, v11, vcc
	global_load_dwordx4 v[10:13], v[14:15], off
	s_nop 0
	global_load_dwordx4 v[14:17], v[14:15], off offset:256
	v_mul_lo_u32 v1, v1, s94
	v_lshlrev_b32_e32 v20, 3, v0
	v_add3_u32 v204, 0, v18, v1
	v_and_b32_e32 v1, 16, v0
	v_bfe_u32 v0, v0, 2, 2
	v_lshl_or_b32 v0, v201, 2, v0
	v_mad_u32_u24 v0, v0, s94, 0
	v_lshlrev_b32_e32 v1, 1, v1
	s_waitcnt vmcnt(3)
	ds_write_b128 v204, v[2:5]
	s_waitcnt vmcnt(2)
	ds_write_b128 v204, v[6:9] offset:18432
	s_waitcnt vmcnt(1)
	ds_write_b128 v204, v[10:13] offset:4608
	s_waitcnt vmcnt(0)
	ds_write_b128 v204, v[14:17] offset:23040
	v_and_b32_e32 v2, 24, v20
	v_add3_u32 v165, v0, v1, v2
	v_mul_u32_u24_e32 v0, 0x90, v202
	v_add3_u32 v160, 0, v160, v0
	v_mov_b32_e32 v0, 0
	v_mov_b32_e32 v1, v0
	v_mov_b32_e32 v2, v0
	v_mov_b32_e32 v3, v0
	v_mov_b32_e32 v4, v0
	v_mov_b32_e32 v5, v0
	v_mov_b32_e32 v6, v0
	v_mov_b32_e32 v7, v0
	v_mov_b32_e32 v8, v0
	v_mov_b32_e32 v9, v0
	v_mov_b32_e32 v10, v0
	v_mov_b32_e32 v11, v0
	v_mov_b32_e32 v12, v0
	v_mov_b32_e32 v13, v0
	v_mov_b32_e32 v14, v0
	v_mov_b32_e32 v15, v0
	v_mov_b32_e32 v32, v0
	v_mov_b32_e32 v33, v0
	v_mov_b32_e32 v34, v0
	v_mov_b32_e32 v35, v0
	v_mov_b32_e32 v36, v0
	v_mov_b32_e32 v37, v0
	v_mov_b32_e32 v38, v0
	v_mov_b32_e32 v39, v0
	v_mov_b32_e32 v40, v0
	v_mov_b32_e32 v41, v0
	v_mov_b32_e32 v42, v0
	v_mov_b32_e32 v43, v0
	v_mov_b32_e32 v44, v0
	v_mov_b32_e32 v45, v0
	v_mov_b32_e32 v46, v0
	v_mov_b32_e32 v47, v0
	v_mov_b32_e32 v16, v0
	v_mov_b32_e32 v17, v0
	v_mov_b32_e32 v18, v0
	v_mov_b32_e32 v19, v0
	v_mov_b32_e32 v20, v0
	v_mov_b32_e32 v21, v0
	v_mov_b32_e32 v22, v0
	v_mov_b32_e32 v23, v0
	v_mov_b32_e32 v24, v0
	v_mov_b32_e32 v25, v0
	v_mov_b32_e32 v26, v0
	v_mov_b32_e32 v27, v0
	v_mov_b32_e32 v28, v0
	v_mov_b32_e32 v29, v0
	v_mov_b32_e32 v30, v0
	v_mov_b32_e32 v31, v0
	v_mov_b32_e32 v48, v0
	v_mov_b32_e32 v49, v0
	v_mov_b32_e32 v50, v0
	v_mov_b32_e32 v51, v0
	v_mov_b32_e32 v52, v0
	v_mov_b32_e32 v53, v0
	v_mov_b32_e32 v54, v0
	v_mov_b32_e32 v55, v0
	v_mov_b32_e32 v56, v0
	v_mov_b32_e32 v57, v0
	v_mov_b32_e32 v58, v0
	v_mov_b32_e32 v59, v0
	v_mov_b32_e32 v60, v0
	v_mov_b32_e32 v61, v0
	v_mov_b32_e32 v62, v0
	v_mov_b32_e32 v63, v0
	v_mov_b32_e32 v154, v0
	v_mov_b32_e32 v155, v0
	s_waitcnt lgkmcnt(0)
	s_barrier
	v_add_u32_e32 v66, s4, v203
	v_add_u32_e32 v64, 64, v66
	v_mad_i64_i32 v[238:239], s[6:7], v64, s12, v[166:167]
	v_add_co_u32_e32 v238, vcc, s13, v238
	s_nop 1
	v_addc_co_u32_e32 v239, vcc, 0, v239, vcc
	v_add_u32_e32 v64, 0x60, v66
	v_mad_i64_i32 v[240:241], s[6:7], v64, s12, v[166:167]
	v_add_co_u32_e32 v240, vcc, s13, v240
	s_nop 1
	v_addc_co_u32_e32 v241, vcc, 0, v241, vcc
	s_mov_b32 s6, 0x62000
	s_mov_b32 s7, 0
; #define LAS __attribute__((address_space(3)))
; DI unsigned pk2(float lo, float hi) { f32x2 v = {lo, hi}; bfv2 b = __builtin_convertvector(v, bfv2); return __builtin_bit_cast(unsigned, b); }
; DI f32x16 mfma32(bf16x8 a, bf16x8 b, f32x16 c) { return __builtin_amdgcn_mfma_f32_32x32x16_bf16(a, b, c, 0, 0, 0); }
; DI void attn_unit(const Params& p, int unit, unsigned char* lds) {
;     ...
;   for (int tl = 0; tl < 64; ++tl) {
;     { const int tn_ = tl + 1 < 64 ? tl + 1 : 63; AT_LOAD(tn_); }
;     asm volatile("" ::: "memory"); __builtin_amdgcn_sched_barrier(0);
;     const bf16_t* k_ = Ks + (tl & 1) * 64 * 72; const bf16_t* v_ = Vs + (tl & 1) * 64 * 72;
; #pragma unroll
;     for (int kt = 0; kt < 2; ++kt) {
;       f32x16 Sx[2];
;       f32x16 zero16;
; #pragma unroll
;       for (int i = 0; i < 16; ++i) zero16[i] = 0.f;
; #pragma unroll
;       for (int ks = 0; ks < 4; ++ks) {
;         const bf16x8 kf = *(const bf16x8*)(k_ + (32 * kt + r) * 72 + 16 * ks + 8 * hh);
; #pragma unroll
;         for (int g = 0; g < 2; ++g) Sx[g] = mfma32(kf, Qf[g][ks], ks == 0 ? zero16 : Sx[g]);
;       }
;       bf16x8 vf[2][2];
; #pragma unroll
;       for (int s = 0; s < 2; ++s)
; #pragma unroll
;         for (int dt = 0; dt < 2; ++dt) {
;           const bf16_t* vb_ = v_ + (32 * kt + 16 * s) * 72 + 32 * dt + troff;
;           const s16x4 lo = __builtin_amdgcn_ds_read_tr16_b64_v4i16((LAS s16x4*)(vb_));
;           const s16x4 hi = __builtin_amdgcn_ds_read_tr16_b64_v4i16((LAS s16x4*)(vb_ + 8 * 72));
;           vf[s][dt] = __builtin_shufflevector(lo, hi, 0, 1, 2, 3, 4, 5, 6, 7);
;         }
; #pragma unroll
;       for (int g = 0; g < 2; ++g) {
;         float pv[16];
; #pragma unroll
;         for (int i = 0; i < 16; ++i) { pv[i] = __builtin_amdgcn_exp2f(Sx[g][i]); lsum[g] += pv[i]; }
;         bf16x8 Pb[2];
; #pragma unroll
;         for (int s = 0; s < 2; ++s) {
;           const u32x4 w = {pk2(pv[8 * s], pv[8 * s + 1]), pk2(pv[8 * s + 2], pv[8 * s + 3]), pk2(pv[8 * s + 4], pv[8 * s + 5]), pk2(pv[8 * s + 6], pv[8 * s + 7])};
;           Pb[s] = __builtin_bit_cast(bf16x8, w);
;         }
; #pragma unroll
;         for (int s = 0; s < 2; ++s)
; #pragma unroll
;           for (int dt = 0; dt < 2; ++dt) O[dt][g] = mfma32(vf[s][dt], Pb[s], O[dt][g]);
.LBB0_99:
	s_add_i32 s5, s4, 64
	global_load_dwordx4 v[128:131], v[238:239], off
	global_load_dwordx4 v[132:135], v[238:239], off offset:256
	global_load_dwordx4 v[136:139], v[240:241], off
	global_load_dwordx4 v[140:143], v[240:241], off offset:256
	v_lshl_add_u64 v[238:239], v[238:239], 0, s[6:7]
	v_lshl_add_u64 v[240:241], v[240:241], 0, s[6:7]
	s_and_b32 s2, s4, 64
	s_mulk_i32 s2, 0x90
	v_add_u32_e32 v205, s2, v160
	ds_read_b128 v[64:67], v205
	ds_read_b128 v[144:147], v205 offset:32
	v_add_u32_e32 v153, s2, v165
	s_and_b32 s2, s5, 64
	s_mulk_i32 s2, 0x90
	s_waitcnt lgkmcnt(1)
	v_mfma_f32_32x32x16_bf16 v[80:95], v[64:67], v[116:119], 0
	s_cmpk_eq_i32 s5, 0xfc0
	s_mov_b32 s4, s5
	v_mfma_f32_32x32x16_bf16 v[64:79], v[64:67], v[124:127], 0
	s_waitcnt lgkmcnt(0)
	v_mfma_f32_32x32x16_bf16 v[80:95], v[144:147], v[108:111], v[80:95]
	v_mfma_f32_32x32x16_bf16 v[64:79], v[144:147], v[120:123], v[64:79]
	ds_read_b128 v[144:147], v205 offset:64
	s_waitcnt lgkmcnt(0)
	v_mfma_f32_32x32x16_bf16 v[80:95], v[144:147], v[100:103], v[80:95]
	v_mfma_f32_32x32x16_bf16 v[64:79], v[144:147], v[112:115], v[64:79]
	ds_read_b128 v[144:147], v205 offset:96
	s_waitcnt lgkmcnt(0)
	v_mfma_f32_32x32x16_bf16 v[80:95], v[144:147], v[96:99], v[80:95]
	v_mfma_f32_32x32x16_bf16 v[64:79], v[144:147], v[104:107], v[64:79]
	s_nop 10
	v_exp_f32_e32 v157, v80
	v_exp_f32_e32 v81, v81
	v_exp_f32_e32 v215, v82
	v_exp_f32_e32 v83, v83
	v_exp_f32_e32 v217, v84
	v_exp_f32_e32 v85, v85
	v_exp_f32_e32 v219, v86
	v_exp_f32_e32 v87, v87
	v_exp_f32_e32 v156, v64
	v_exp_f32_e32 v80, v65
	v_exp_f32_e32 v214, v66
	ds_read_b64_tr_b16 v[206:207], v153 offset:18432
	ds_read_b64_tr_b16 v[208:209], v153 offset:19584
	ds_read_b64_tr_b16 v[210:211], v153 offset:18496
	ds_read_b64_tr_b16 v[212:213], v153 offset:19648
	ds_read_b64_tr_b16 v[144:145], v153 offset:20736
	ds_read_b64_tr_b16 v[146:147], v153 offset:21888
	ds_read_b64_tr_b16 v[148:149], v153 offset:20800
	ds_read_b64_tr_b16 v[150:151], v153 offset:21952
	v_exp_f32_e32 v82, v67
	v_cvt_pk_bf16_f32 v64, v157, v81
	v_cvt_pk_bf16_f32 v65, v215, v83
	v_cvt_pk_bf16_f32 v66, v217, v85
	v_cvt_pk_bf16_f32 v67, v219, v87
	v_exp_f32_e32 v216, v68
	v_exp_f32_e32 v84, v69
	s_waitcnt lgkmcnt(6)
	v_mfma_f32_32x32x16_bf16 v[48:63], v[206:209], v[64:67], v[48:63]
	v_exp_f32_e32 v218, v70
	v_exp_f32_e32 v86, v71
	v_exp_f32_e32 v221, v88
	v_exp_f32_e32 v220, v72
	v_exp_f32_e32 v89, v89
	v_exp_f32_e32 v88, v73
	v_exp_f32_e32 v159, v90
	s_waitcnt lgkmcnt(4)
	v_mfma_f32_32x32x16_bf16 v[32:47], v[210:213], v[64:67], v[32:47]
	v_add_f32_e64 v64, v154, v156
	v_add_f32_e64 v65, v155, v157
	v_cvt_pk_bf16_f32 v66, v216, v84
	v_add_f32_e64 v64, v80, v64
	v_add_f32_e64 v65, v81, v65
	v_cvt_pk_bf16_f32 v67, v218, v86
	v_add_f32_e32 v64, v214, v64
	v_add_f32_e32 v65, v215, v65
	v_exp_f32_e32 v171, v91
	v_add_f32_e32 v64, v82, v64
	v_add_f32_e32 v65, v83, v65
	v_exp_f32_e32 v169, v92
	v_add_f32_e32 v64, v216, v64
	v_add_f32_e32 v65, v217, v65
	v_exp_f32_e32 v175, v93
	v_add_f32_e32 v64, v84, v64
	v_add_f32_e32 v65, v85, v65
	v_exp_f32_e32 v173, v94
	v_add_f32_e32 v64, v218, v64
	v_add_f32_e32 v65, v219, v65
	v_exp_f32_e32 v177, v95
	v_add_f32_e32 v64, v86, v64
	v_add_f32_e32 v65, v87, v65
	v_cvt_pk_bf16_f32 v152, v221, v89
	v_add_f32_e32 v64, v220, v64
	v_add_f32_e32 v65, v221, v65
	v_exp_f32_e32 v158, v74
	v_add_f32_e32 v178, v88, v64
	v_add_f32_e32 v179, v89, v65
	v_cvt_pk_bf16_f32 v64, v156, v80
	v_cvt_pk_bf16_f32 v65, v214, v82
	v_exp_f32_e32 v170, v75
	v_exp_f32_e32 v168, v76
	v_mfma_f32_32x32x16_bf16 v[16:31], v[206:209], v[64:67], v[16:31]
	ds_read_b128 v[206:209], v205 offset:4640
	v_exp_f32_e32 v174, v77
	v_exp_f32_e32 v172, v78
	v_exp_f32_e32 v176, v79
	v_cvt_pk_bf16_f32 v156, v220, v88
	v_cvt_pk_bf16_f32 v154, v169, v175
	v_cvt_pk_bf16_f32 v155, v173, v177
	v_mfma_f32_32x32x16_bf16 v[0:15], v[210:213], v[64:67], v[0:15]
	ds_read_b128 v[64:67], v205 offset:4608
	v_cvt_pk_bf16_f32 v157, v158, v170
	s_waitcnt lgkmcnt(0)
	v_mfma_f32_32x32x16_bf16 v[80:95], v[64:67], v[116:119], 0
	v_mfma_f32_32x32x16_bf16 v[64:79], v[64:67], v[124:127], 0
	v_mfma_f32_32x32x16_bf16 v[80:95], v[206:209], v[108:111], v[80:95]
	v_mfma_f32_32x32x16_bf16 v[64:79], v[206:209], v[120:123], v[64:79]
	ds_read_b128 v[206:209], v205 offset:4672
	s_waitcnt lgkmcnt(0)
	v_mfma_f32_32x32x16_bf16 v[80:95], v[206:209], v[100:103], v[80:95]
	v_mfma_f32_32x32x16_bf16 v[64:79], v[206:209], v[112:115], v[64:79]
	ds_read_b128 v[206:209], v205 offset:4704
	s_waitcnt lgkmcnt(0)
; #define LAS __attribute__((address_space(3)))
; DI unsigned pk2(float lo, float hi) { f32x2 v = {lo, hi}; bfv2 b = __builtin_convertvector(v, bfv2); return __builtin_bit_cast(unsigned, b); }
; DI f32x16 mfma32(bf16x8 a, bf16x8 b, f32x16 c) { return __builtin_amdgcn_mfma_f32_32x32x16_bf16(a, b, c, 0, 0, 0); }
; #define AT_STORE(buf_) do { _Pragma("unroll") for (int i_ = 0; i_ < 2; ++i_) { *(u32x4*)(Ks + (buf_) * 64 * 72 + (skey + 32 * i_) * 72 + sdc) = rk[i_]; \
;     *(u32x4*)(Vs + (buf_) * 64 * 72 + (skey + 32 * i_) * 72 + sdc) = rv[i_]; } } while (0)
; DI void attn_unit(const Params& p, int unit, unsigned char* lds) {
;     ...
;     for (int kt = 0; kt < 2; ++kt) {
;       f32x16 Sx[2];
;       f32x16 zero16;
; #pragma unroll
;       for (int i = 0; i < 16; ++i) zero16[i] = 0.f;
; #pragma unroll
;       for (int ks = 0; ks < 4; ++ks) {
;         const bf16x8 kf = *(const bf16x8*)(k_ + (32 * kt + r) * 72 + 16 * ks + 8 * hh);
; #pragma unroll
;         for (int g = 0; g < 2; ++g) Sx[g] = mfma32(kf, Qf[g][ks], ks == 0 ? zero16 : Sx[g]);
;       }
;       bf16x8 vf[2][2];
; #pragma unroll
;       for (int s = 0; s < 2; ++s)
; #pragma unroll
;         for (int dt = 0; dt < 2; ++dt) {
;           const bf16_t* vb_ = v_ + (32 * kt + 16 * s) * 72 + 32 * dt + troff;
;           const s16x4 lo = __builtin_amdgcn_ds_read_tr16_b64_v4i16((LAS s16x4*)(vb_));
;           const s16x4 hi = __builtin_amdgcn_ds_read_tr16_b64_v4i16((LAS s16x4*)(vb_ + 8 * 72));
;           vf[s][dt] = __builtin_shufflevector(lo, hi, 0, 1, 2, 3, 4, 5, 6, 7);
;         }
; #pragma unroll
;       for (int g = 0; g < 2; ++g) {
;         float pv[16];
; #pragma unroll
;         for (int i = 0; i < 16; ++i) { pv[i] = __builtin_amdgcn_exp2f(Sx[g][i]); lsum[g] += pv[i]; }
;         bf16x8 Pb[2];
; #pragma unroll
;         for (int s = 0; s < 2; ++s) {
;           const u32x4 w = {pk2(pv[8 * s], pv[8 * s + 1]), pk2(pv[8 * s + 2], pv[8 * s + 3]), pk2(pv[8 * s + 4], pv[8 * s + 5]), pk2(pv[8 * s + 6], pv[8 * s + 7])};
;           Pb[s] = __builtin_bit_cast(bf16x8, w);
;         }
; #pragma unroll
;         for (int s = 0; s < 2; ++s)
; #pragma unroll
;           for (int dt = 0; dt < 2; ++dt) O[dt][g] = mfma32(vf[s][dt], Pb[s], O[dt][g]);
;       }
;     }
;     if (tl + 1 < 64) AT_STORE((tl + 1) & 1);
;     __syncthreads();
	v_mfma_f32_32x32x16_bf16 v[80:95], v[206:209], v[96:99], v[80:95]
	v_mfma_f32_32x32x16_bf16 v[64:79], v[206:209], v[104:107], v[64:79]
	s_nop 10
	v_exp_f32_e32 v223, v80
	v_exp_f32_e32 v81, v81
	ds_read_b64_tr_b16 v[206:207], v153 offset:23040
	ds_read_b64_tr_b16 v[208:209], v153 offset:24192
	ds_read_b64_tr_b16 v[210:211], v153 offset:23104
	ds_read_b64_tr_b16 v[212:213], v153 offset:24256
	ds_read_b64_tr_b16 v[214:215], v153 offset:25344
	ds_read_b64_tr_b16 v[216:217], v153 offset:26496
	ds_read_b64_tr_b16 v[218:219], v153 offset:25408
	ds_read_b64_tr_b16 v[220:221], v153 offset:26560
	v_exp_f32_e32 v225, v82
	v_cvt_pk_bf16_f32 v153, v159, v171
	v_exp_f32_e32 v83, v83
	v_exp_f32_e32 v227, v84
	v_exp_f32_e32 v222, v64
	v_exp_f32_e32 v80, v65
	v_add_f32_e32 v64, v158, v178
	v_add_f32_e32 v65, v159, v179
	v_exp_f32_e32 v224, v66
	v_add_f32_e32 v64, v170, v64
	v_add_f32_e32 v65, v171, v65
	v_exp_f32_e32 v82, v67
	v_add_f32_e32 v64, v168, v64
	v_add_f32_e32 v65, v169, v65
	v_mfma_f32_32x32x16_bf16 v[48:63], v[144:147], v[152:155], v[48:63]
	v_add_f32_e64 v64, v174, v64
	v_add_f32_e64 v65, v175, v65
	v_cvt_pk_bf16_f32 v158, v168, v174
	v_add_f32_e64 v64, v172, v64
	v_add_f32_e64 v65, v173, v65
	v_cvt_pk_bf16_f32 v159, v172, v176
	v_exp_f32_e32 v226, v68
	v_exp_f32_e32 v85, v85
	v_exp_f32_e32 v84, v69
	v_mfma_f32_32x32x16_bf16 v[32:47], v[148:151], v[152:155], v[32:47]
	v_add_f32_e64 v152, v176, v64
	v_add_f32_e64 v153, v177, v65
	v_exp_f32_e32 v229, v86
	v_exp_f32_e32 v87, v87
	v_exp_f32_e32 v228, v70
	v_exp_f32_e32 v86, v71
	v_exp_f32_e32 v231, v88
	v_exp_f32_e32 v230, v72
	v_mfma_f32_32x32x16_bf16 v[16:31], v[144:147], v[156:159], v[16:31]
	v_add_f32_e64 v144, v152, v222
	v_add_f32_e64 v145, v153, v223
	v_exp_f32_e32 v89, v89
	v_add_f32_e32 v144, v80, v144
	v_add_f32_e32 v145, v81, v145
	v_exp_f32_e32 v88, v73
	v_add_f32_e32 v144, v224, v144
	v_add_f32_e32 v145, v225, v145
	v_exp_f32_e32 v233, v90
	v_add_f32_e32 v144, v82, v144
	v_add_f32_e32 v145, v83, v145
	v_mfma_f32_32x32x16_bf16 v[0:15], v[148:151], v[156:159], v[0:15]
	v_add_f32_e64 v144, v226, v144
	v_add_f32_e64 v145, v227, v145
	v_cvt_pk_bf16_f32 v64, v223, v81
	v_add_f32_e64 v68, v84, v144
	v_add_f32_e64 v69, v85, v145
	v_cvt_pk_bf16_f32 v65, v225, v83
	v_cvt_pk_bf16_f32 v66, v227, v85
	v_exp_f32_e32 v232, v74
	v_add_f32_e32 v68, v228, v68
	v_add_f32_e32 v69, v229, v69
	v_cvt_pk_bf16_f32 v67, v229, v87
	v_exp_f32_e32 v91, v91
	v_exp_f32_e32 v90, v75
	v_add_f32_e32 v68, v86, v68
	v_add_f32_e32 v69, v87, v69
	s_waitcnt lgkmcnt(6)
	v_mfma_f32_32x32x16_bf16 v[48:63], v[206:209], v[64:67], v[48:63]
	v_exp_f32_e32 v235, v92
	v_exp_f32_e32 v234, v76
	v_add_f32_e32 v68, v230, v68
	v_add_f32_e32 v69, v231, v69
	v_exp_f32_e32 v93, v93
	v_exp_f32_e32 v92, v77
	v_add_f32_e32 v68, v88, v68
	v_add_f32_e32 v69, v89, v69
	v_exp_f32_e32 v237, v94
	s_waitcnt lgkmcnt(4)
	v_mfma_f32_32x32x16_bf16 v[32:47], v[210:213], v[64:67], v[32:47]
	v_cvt_pk_bf16_f32 v64, v222, v80
	v_cvt_pk_bf16_f32 v65, v224, v82
	v_cvt_pk_bf16_f32 v66, v226, v84
	v_cvt_pk_bf16_f32 v67, v228, v86
	v_exp_f32_e32 v95, v95
	v_exp_f32_e32 v236, v78
	v_add_f32_e32 v68, v232, v68
	v_add_f32_e32 v69, v233, v69
	v_mfma_f32_32x32x16_bf16 v[16:31], v[206:209], v[64:67], v[16:31]
	v_exp_f32_e32 v94, v79
	v_add_f32_e32 v68, v90, v68
	v_add_f32_e32 v69, v91, v69
	v_cvt_pk_bf16_f32 v70, v235, v93
	v_add_f32_e32 v68, v234, v68
	v_add_f32_e32 v69, v235, v69
	v_cvt_pk_bf16_f32 v71, v237, v95
	v_add_f32_e32 v68, v92, v68
	v_add_f32_e32 v69, v93, v69
	v_mfma_f32_32x32x16_bf16 v[0:15], v[210:213], v[64:67], v[0:15]
	v_add_f32_e64 v72, v236, v68
	v_add_f32_e64 v73, v237, v69
	v_cvt_pk_bf16_f32 v68, v231, v89
	v_cvt_pk_bf16_f32 v69, v233, v91
	v_add_f32_e64 v154, v94, v72
	v_add_f32_e64 v155, v95, v73
	v_add_u32_e32 v64, s2, v204
	s_waitcnt vmcnt(3)
	ds_write_b128 v64, v[128:131]
	s_waitcnt vmcnt(2)
	ds_write_b128 v64, v[132:135] offset:18432
	s_waitcnt vmcnt(1)
	ds_write_b128 v64, v[136:139] offset:4608
	s_waitcnt vmcnt(0)
	ds_write_b128 v64, v[140:143] offset:23040
	s_waitcnt lgkmcnt(0)
	v_mfma_f32_32x32x16_bf16 v[48:63], v[214:217], v[68:71], v[48:63]
	s_barrier
	v_mfma_f32_32x32x16_bf16 v[32:47], v[218:221], v[68:71], v[32:47]
	v_cvt_pk_bf16_f32 v68, v230, v88
	v_cvt_pk_bf16_f32 v69, v232, v90
	v_cvt_pk_bf16_f32 v70, v234, v92
	v_cvt_pk_bf16_f32 v71, v236, v94
	s_nop 1
	v_mfma_f32_32x32x16_bf16 v[16:31], v[214:217], v[68:71], v[16:31]
	v_mfma_f32_32x32x16_bf16 v[0:15], v[218:221], v[68:71], v[0:15]
	s_cbranch_scc0 .LBB0_99
; #define LAS __attribute__((address_space(3)))
; DI unsigned pk2(float lo, float hi) { f32x2 v = {lo, hi}; bfv2 b = __builtin_convertvector(v, bfv2); return __builtin_bit_cast(unsigned, b); }
; DI f32x16 mfma32(bf16x8 a, bf16x8 b, f32x16 c) { return __builtin_amdgcn_mfma_f32_32x32x16_bf16(a, b, c, 0, 0, 0); }
; DI void attn_unit(const Params& p, int unit, unsigned char* lds) {
;     ...
;     const bf16_t* k_ = Ks + (tl & 1) * 64 * 72; const bf16_t* v_ = Vs + (tl & 1) * 64 * 72;
; #pragma unroll
;     for (int kt = 0; kt < 2; ++kt) {
;       f32x16 Sx[2];
;       f32x16 zero16;
; #pragma unroll
;       for (int i = 0; i < 16; ++i) zero16[i] = 0.f;
; #pragma unroll
;       for (int ks = 0; ks < 4; ++ks) {
;         const bf16x8 kf = *(const bf16x8*)(k_ + (32 * kt + r) * 72 + 16 * ks + 8 * hh);
; #pragma unroll
;         for (int g = 0; g < 2; ++g) Sx[g] = mfma32(kf, Qf[g][ks], ks == 0 ? zero16 : Sx[g]);
;       }
;       bf16x8 vf[2][2];
; #pragma unroll
;       for (int s = 0; s < 2; ++s)
; #pragma unroll
;         for (int dt = 0; dt < 2; ++dt) {
;           const bf16_t* vb_ = v_ + (32 * kt + 16 * s) * 72 + 32 * dt + troff;
;           const s16x4 lo = __builtin_amdgcn_ds_read_tr16_b64_v4i16((LAS s16x4*)(vb_));
;           const s16x4 hi = __builtin_amdgcn_ds_read_tr16_b64_v4i16((LAS s16x4*)(vb_ + 8 * 72));
;           vf[s][dt] = __builtin_shufflevector(lo, hi, 0, 1, 2, 3, 4, 5, 6, 7);
;         }
; #pragma unroll
;       for (int g = 0; g < 2; ++g) {
;         float pv[16];
; #pragma unroll
;         for (int i = 0; i < 16; ++i) { pv[i] = __builtin_amdgcn_exp2f(Sx[g][i]); lsum[g] += pv[i]; }
;         bf16x8 Pb[2];
; #pragma unroll
;         for (int s = 0; s < 2; ++s) {
;           const u32x4 w = {pk2(pv[8 * s], pv[8 * s + 1]), pk2(pv[8 * s + 2], pv[8 * s + 3]), pk2(pv[8 * s + 4], pv[8 * s + 5]), pk2(pv[8 * s + 6], pv[8 * s + 7])};
;           Pb[s] = __builtin_bit_cast(bf16x8, w);
;         }
; #pragma unroll
;         for (int s = 0; s < 2; ++s)
; #pragma unroll
;           for (int dt = 0; dt < 2; ++dt) O[dt][g] = mfma32(vf[s][dt], Pb[s], O[dt][g]);
;       }
;     }
;     if (tl + 1 < 64) AT_STORE((tl + 1) & 1);
;     __syncthreads();
;   }
;     ...
;   const int pcol = kvc == 0 ? A_V : (kvc == 1 ? A_Z : (kvc == 2 ? B_V : D_X));
	ds_read_b128 v[64:67], v160 offset:9216
	ds_read_b128 v[128:131], v160 offset:9248
	s_cmp_lt_i32 s34, 1
	s_mov_b64 s[8:9], 0x100
	s_waitcnt lgkmcnt(1)
	v_mfma_f32_32x32x16_bf16 v[80:95], v[64:67], v[116:119], 0
	v_mfma_f32_32x32x16_bf16 v[64:79], v[64:67], v[124:127], 0
	s_waitcnt lgkmcnt(0)
	v_mfma_f32_32x32x16_bf16 v[80:95], v[128:131], v[108:111], v[80:95]
	v_mfma_f32_32x32x16_bf16 v[64:79], v[128:131], v[120:123], v[64:79]
	ds_read_b128 v[128:131], v160 offset:9280
	s_waitcnt lgkmcnt(0)
	v_mfma_f32_32x32x16_bf16 v[80:95], v[128:131], v[100:103], v[80:95]
	v_mfma_f32_32x32x16_bf16 v[64:79], v[128:131], v[112:115], v[64:79]
	ds_read_b128 v[128:131], v160 offset:9312
	ds_read_b64_tr_b16 v[168:169], v165 offset:27648
	ds_read_b64_tr_b16 v[170:171], v165 offset:28800
	ds_read_b64_tr_b16 v[172:173], v165 offset:27712
	ds_read_b64_tr_b16 v[174:175], v165 offset:28864
	ds_read_b64_tr_b16 v[176:177], v165 offset:29952
	ds_read_b64_tr_b16 v[178:179], v165 offset:31104
	ds_read_b64_tr_b16 v[204:205], v165 offset:30016
	ds_read_b64_tr_b16 v[206:207], v165 offset:31168
	s_waitcnt lgkmcnt(8)
	v_mfma_f32_32x32x16_bf16 v[64:79], v[128:131], v[104:107], v[64:79]
	v_mfma_f32_32x32x16_bf16 v[80:95], v[128:131], v[96:99], v[80:95]
	s_nop 10
	v_exp_f32_e32 v128, v64
	v_exp_f32_e32 v129, v65
	v_exp_f32_e32 v130, v66
	v_exp_f32_e32 v131, v67
	v_exp_f32_e32 v132, v68
	v_exp_f32_e32 v133, v69
	v_exp_f32_e32 v134, v70
	v_exp_f32_e32 v135, v71
	v_exp_f32_e32 v144, v80
	v_exp_f32_e32 v145, v81
	v_exp_f32_e32 v146, v82
	v_exp_f32_e32 v147, v83
	v_exp_f32_e32 v148, v84
	v_exp_f32_e32 v149, v85
	v_exp_f32_e32 v150, v86
	v_exp_f32_e32 v151, v87
	v_cvt_pk_bf16_f32 v64, v128, v129
	v_cvt_pk_bf16_f32 v65, v130, v131
	v_cvt_pk_bf16_f32 v66, v132, v133
	v_cvt_pk_bf16_f32 v67, v134, v135
	v_cvt_pk_bf16_f32 v80, v144, v145
	v_cvt_pk_bf16_f32 v81, v146, v147
	v_cvt_pk_bf16_f32 v82, v148, v149
	v_cvt_pk_bf16_f32 v83, v150, v151
	s_waitcnt lgkmcnt(6)
	v_mfma_f32_32x32x16_bf16 v[16:31], v[168:171], v[64:67], v[16:31]
	v_exp_f32_e32 v152, v88
	v_exp_f32_e32 v153, v89
	v_exp_f32_e32 v156, v90
	v_exp_f32_e32 v157, v91
	v_exp_f32_e32 v158, v92
	v_exp_f32_e32 v159, v93
	v_exp_f32_e32 v166, v94
	s_waitcnt lgkmcnt(4)
	v_mfma_f32_32x32x16_bf16 v[0:15], v[172:175], v[64:67], v[0:15]
	ds_read_b128 v[64:67], v160 offset:13824
	v_exp_f32_e32 v167, v95
	v_cvt_pk_bf16_f32 v84, v152, v153
	v_cvt_pk_bf16_f32 v85, v156, v157
	v_cvt_pk_bf16_f32 v86, v158, v159
	v_cvt_pk_bf16_f32 v87, v166, v167
	v_exp_f32_e32 v136, v72
	v_mfma_f32_32x32x16_bf16 v[48:63], v[168:171], v[80:83], v[48:63]
	v_exp_f32_e32 v137, v73
	v_exp_f32_e32 v138, v74
	v_exp_f32_e32 v139, v75
	v_exp_f32_e32 v140, v76
	v_exp_f32_e32 v141, v77
	v_exp_f32_e32 v142, v78
	v_exp_f32_e32 v143, v79
	v_mfma_f32_32x32x16_bf16 v[32:47], v[172:175], v[80:83], v[32:47]
	v_cvt_pk_bf16_f32 v68, v136, v137
	v_cvt_pk_bf16_f32 v69, v138, v139
	v_cvt_pk_bf16_f32 v70, v140, v141
	v_cvt_pk_bf16_f32 v71, v142, v143
	s_waitcnt lgkmcnt(3)
	v_mfma_f32_32x32x16_bf16 v[48:63], v[176:179], v[84:87], v[48:63]
	s_waitcnt lgkmcnt(1)
	v_mfma_f32_32x32x16_bf16 v[32:47], v[204:207], v[84:87], v[32:47]
	s_waitcnt lgkmcnt(0)
	v_mfma_f32_32x32x16_bf16 v[80:95], v[64:67], v[116:119], 0
	ds_read_b128 v[116:119], v160 offset:13856
	v_mfma_f32_32x32x16_bf16 v[16:31], v[176:179], v[68:71], v[16:31]
	v_mfma_f32_32x32x16_bf16 v[0:15], v[204:207], v[68:71], v[0:15]
	v_mfma_f32_32x32x16_bf16 v[64:79], v[64:67], v[124:127], 0
	s_waitcnt lgkmcnt(0)
	v_mfma_f32_32x32x16_bf16 v[80:95], v[116:119], v[108:111], v[80:95]
	ds_read_b128 v[108:111], v160 offset:13888
	v_mfma_f32_32x32x16_bf16 v[64:79], v[116:119], v[120:123], v[64:79]
	s_waitcnt lgkmcnt(0)
	v_mfma_f32_32x32x16_bf16 v[80:95], v[108:111], v[100:103], v[80:95]
	ds_read_b128 v[100:103], v160 offset:13920
	v_mfma_f32_32x32x16_bf16 v[64:79], v[108:111], v[112:115], v[64:79]
	s_waitcnt lgkmcnt(0)
	v_mfma_f32_32x32x16_bf16 v[80:95], v[100:103], v[96:99], v[80:95]
	v_mfma_f32_32x32x16_bf16 v[64:79], v[100:103], v[104:107], v[64:79]
	s_nop 10
	v_exp_f32_e32 v80, v80
	v_exp_f32_e32 v81, v81
	v_exp_f32_e32 v82, v82
	v_exp_f32_e32 v83, v83
	v_exp_f32_e32 v84, v84
	v_exp_f32_e32 v85, v85
	v_exp_f32_e32 v86, v86
	v_exp_f32_e32 v87, v87
	ds_read_b64_tr_b16 v[108:109], v165 offset:32256
	ds_read_b64_tr_b16 v[110:111], v165 offset:33408
	ds_read_b64_tr_b16 v[104:105], v165 offset:32320
	ds_read_b64_tr_b16 v[106:107], v165 offset:33472
	ds_read_b64_tr_b16 v[96:97], v165 offset:34560
	ds_read_b64_tr_b16 v[98:99], v165 offset:35712
	ds_read_b64_tr_b16 v[100:101], v165 offset:34624
	ds_read_b64_tr_b16 v[102:103], v165 offset:35776
	v_cvt_pk_bf16_f32 v112, v80, v81
	v_cvt_pk_bf16_f32 v113, v82, v83
	v_cvt_pk_bf16_f32 v114, v84, v85
	v_cvt_pk_bf16_f32 v115, v86, v87
	v_exp_f32_e32 v68, v68
	v_exp_f32_e32 v69, v69
	s_waitcnt lgkmcnt(6)
	v_mfma_f32_32x32x16_bf16 v[48:63], v[108:111], v[112:115], v[48:63]
	v_exp_f32_e32 v70, v70
	v_exp_f32_e32 v71, v71
	v_exp_f32_e32 v88, v88
	v_exp_f32_e32 v89, v89
	v_exp_f32_e32 v90, v90
	v_exp_f32_e32 v91, v91
	v_exp_f32_e32 v92, v92
	s_waitcnt lgkmcnt(4)
	v_mfma_f32_32x32x16_bf16 v[32:47], v[104:107], v[112:115], v[32:47]
	v_exp_f32_e32 v112, v64
	v_exp_f32_e32 v113, v65
	v_exp_f32_e32 v114, v66
	v_exp_f32_e32 v115, v67
	v_cvt_pk_bf16_f32 v66, v68, v69
	v_cvt_pk_bf16_f32 v64, v112, v113
	v_cvt_pk_bf16_f32 v67, v70, v71
	v_cvt_pk_bf16_f32 v65, v114, v115
	v_exp_f32_e32 v93, v93
	v_exp_f32_e32 v94, v94
	v_mfma_f32_32x32x16_bf16 v[16:31], v[108:111], v[64:67], v[16:31]
	v_exp_f32_e32 v95, v95
	v_exp_f32_e32 v72, v72
	v_exp_f32_e32 v73, v73
	v_exp_f32_e32 v74, v74
	v_exp_f32_e32 v75, v75
	v_exp_f32_e32 v76, v76
	v_exp_f32_e32 v77, v77
	v_mfma_f32_32x32x16_bf16 v[0:15], v[104:107], v[64:67], v[0:15]
	v_exp_f32_e32 v78, v78
	v_exp_f32_e32 v79, v79
	v_cvt_pk_bf16_f32 v116, v88, v89
	v_cvt_pk_bf16_f32 v117, v90, v91
	v_cvt_pk_bf16_f32 v118, v92, v93
	v_cvt_pk_bf16_f32 v119, v94, v95
	s_waitcnt lgkmcnt(0)
	s_barrier
	v_mfma_f32_32x32x16_bf16 v[48:63], v[96:99], v[116:119], v[48:63]
	v_mfma_f32_32x32x16_bf16 v[32:47], v[100:103], v[116:119], v[32:47]
	v_cvt_pk_bf16_f32 v116, v72, v73
	v_cvt_pk_bf16_f32 v117, v74, v75
	v_cvt_pk_bf16_f32 v118, v76, v77
	v_cvt_pk_bf16_f32 v119, v78, v79
	s_nop 1
	v_mfma_f32_32x32x16_bf16 v[16:31], v[96:99], v[116:119], v[16:31]
	v_mfma_f32_32x32x16_bf16 v[0:15], v[100:103], v[116:119], v[0:15]
	s_cbranch_scc1 .LBB0_105
	s_cmp_lg_u32 s34, 1
	s_mov_b64 s[4:5], -1
	s_cbranch_scc0 .LBB0_103
	s_cmp_eq_u32 s34, 2
	s_cselect_b32 s84, s45, 0xa00
	s_mov_b64 s[4:5], 0
	s_mov_b64 s[8:9], s[84:85]
